# attention phases: static priority raise moved to waves 0-3 instead of waves 4-7
# baseline (speedup 1.0000x reference)
; __global__ void __launch_bounds__(512, 2) mega(Params p) {
;     ...
;     for (int rp = 0; rp < REP_P2; ++rp)
;     for (int item = bid; item < 512; item += nb) {
.LBB0_631:
	v_readfirstlane_b32 s100, v224
	s_nop 0
	s_cmpk_lt_u32 s100, 0x100
	s_cbranch_scc0 .Lprio_p2
	s_setprio 1

; DI void xcd_barrier(const XcdBarrier& b) {
;     ...
;   __syncthreads();
; __global__ void __launch_bounds__(512, 2) mega(Params p) {
;     ...
;     for (int rp = 0; rp < REP_P4; ++rp)
;     for (int item = bid; item < 256; item += nb) {
.LBB0_1072:
	s_or_b64 exec, exec, s[0:1]
	v_readlane_b32 s0, v253, 38
	v_readlane_b32 s1, v253, 39
	s_andn2_b64 vcc, exec, s[0:1]
	v_readlane_b32 s14, v252, 0
	s_waitcnt lgkmcnt(0)
	s_barrier
	v_readfirstlane_b32 s100, v224
	s_nop 0
	s_cmpk_lt_u32 s100, 0x100
	s_cbranch_scc0 .Lprio_p5
	s_setprio 1
